# MLA loop single barrier per tile with hoisted global loads (K/KR LDS writes inside PV), plus previous changes
# baseline (speedup 1.0000x reference)
.LBB0_762:
	ds_read_b128 v[64:67], v189 offset:49152
	ds_read_b128 v[68:71], v189 offset:57344
	ds_read_b128 v[236:239], v191 offset:49152
	ds_read_b128 v[240:243], v191 offset:57344
	ds_read_b128 v[244:247], v193 offset:49152
	ds_read_b128 v[248:251], v193 offset:57344
	s_add_i32 s9, s24, -1
	s_cmp_lt_u32 s9, 3
	s_cselect_b32 s100, s46, s68
	s_add_i32 s100, s100, s8
	s_ashr_i32 s101, s100, 31
	s_add_i32 s0, 0, 0x12800
	s_waitcnt lgkmcnt(5)
	v_mfma_f32_32x32x16_bf16 v[80:95], v[64:67], v[124:127], 0
	v_exp_f32_e32 v140, v140
	v_exp_f32_e32 v141, v141
	v_exp_f32_e32 v138, v138
	v_exp_f32_e32 v139, v139
	s_waitcnt lgkmcnt(4)
	v_mfma_f32_32x32x16_bf16 v[64:79], v[68:71], v[124:127], 0
	v_exp_f32_e32 v214, v130
	v_exp_f32_e32 v215, v131
	v_exp_f32_e32 v142, v142
	v_exp_f32_e32 v143, v143
	s_waitcnt lgkmcnt(3)
	v_mfma_f32_32x32x16_bf16 v[80:95], v[236:239], v[120:123], v[80:95]
	ds_read_b128 v[236:239], v195 offset:49152
	v_exp_f32_e32 v136, v136
	v_exp_f32_e32 v137, v137
	v_add_u32_e32 v211, s0, v198
	v_add_u32_e32 v210, s0, v200
	v_exp_f32_e32 v212, v132
	s_waitcnt lgkmcnt(3)
	v_mfma_f32_32x32x16_bf16 v[64:79], v[240:243], v[120:123], v[64:79]
	ds_read_b128 v[240:243], v195 offset:57344
	v_exp_f32_e32 v213, v133
	v_add_u32_e32 v216, s0, v202
	v_add_u32_e32 v217, s0, v204
	v_exp_f32_e32 v220, v128
	v_add_f32_e32 v128, 0, v159
	v_add_f32_e32 v128, v161, v128
	s_waitcnt lgkmcnt(3)
	v_mfma_f32_32x32x16_bf16 v[80:95], v[244:247], v[116:119], v[80:95]
	ds_read_b128 v[244:247], v196 offset:49152
	v_add_f32_e32 v128, v157, v128
	v_add_f32_e32 v128, v160, v128
	v_add_f32_e32 v128, v156, v128
	v_add_f32_e32 v128, v158, v128
	v_add_f32_e32 v128, v154, v128
	v_add_f32_e32 v128, v155, v128
	v_add_f32_e32 v128, v151, v128
	v_add_f32_e32 v128, v153, v128
	s_waitcnt lgkmcnt(3)
	v_mfma_f32_32x32x16_bf16 v[64:79], v[248:251], v[116:119], v[64:79]
	ds_read_b128 v[248:251], v196 offset:57344
	v_add_f32_e32 v128, v150, v128
	v_add_f32_e32 v128, v152, v128
	v_add_f32_e32 v128, v147, v128
	v_add_f32_e32 v128, v149, v128
	v_add_f32_e32 v128, v146, v128
	v_add_f32_e32 v128, v148, v128
	v_add_f32_e32 v128, v140, v128
	v_add_f32_e32 v128, v141, v128
	s_waitcnt lgkmcnt(3)
	v_mfma_f32_32x32x16_bf16 v[80:95], v[236:239], v[112:115], v[80:95]
	ds_read_b128 v[236:239], v194 offset:49152
	v_add_f32_e32 v128, v138, v128
	v_add_f32_e32 v128, v139, v128
	v_add_f32_e32 v128, v212, v128
	v_exp_f32_e32 v221, v129
	v_add_f32_e32 v128, v213, v128
	v_add_f32_e32 v128, v214, v128
	v_add_f32_e32 v128, v215, v128
	s_waitcnt lgkmcnt(3)
	v_mfma_f32_32x32x16_bf16 v[64:79], v[240:243], v[112:115], v[64:79]
	ds_read_b128 v[240:243], v194 offset:57344
	v_add_f32_e32 v128, v220, v128
	v_add_f32_e32 v128, v221, v128
	v_exp_f32_e32 v223, v134
	v_add_f32_e32 v128, v142, v128
	v_exp_f32_e32 v224, v135
	v_add_f32_e32 v128, v143, v128
	s_waitcnt lgkmcnt(3)
	v_mfma_f32_32x32x16_bf16 v[80:95], v[244:247], v[108:111], v[80:95]
	ds_read_b128 v[244:247], v192 offset:49152
	v_add_f32_e32 v128, v136, v128
	v_add_f32_e32 v128, v137, v128
	v_add_f32_e32 v128, v223, v128
	v_add_f32_e32 v218, v224, v128
	v_mov_b32_e32 v219, v218
	v_cvt_pk_bf16_f32 v128, v159, v161
	v_cvt_pk_bf16_f32 v129, v157, v160
	v_cvt_pk_bf16_f32 v130, v156, v158
	s_waitcnt lgkmcnt(3)
	v_mfma_f32_32x32x16_bf16 v[64:79], v[248:251], v[108:111], v[64:79]
	ds_read_b128 v[248:251], v192 offset:57344
	v_cvt_pk_bf16_f32 v131, v154, v155
	v_cvt_pk_bf16_f32 v132, v151, v153
	v_cvt_pk_bf16_f32 v133, v150, v152
	v_cvt_pk_bf16_f32 v134, v147, v149
	v_cvt_pk_bf16_f32 v135, v146, v148
	v_cvt_pk_bf16_f32 v154, v140, v141
	v_cvt_pk_bf16_f32 v155, v138, v139
	v_cvt_pk_bf16_f32 v156, v212, v213
	s_waitcnt lgkmcnt(3)
	v_mfma_f32_32x32x16_bf16 v[80:95], v[236:239], v[104:107], v[80:95]
	ds_read_b128 v[236:239], v190 offset:49152
	v_cvt_pk_bf16_f32 v157, v214, v215
	v_cvt_pk_bf16_f32 v220, v220, v221
	v_cvt_pk_bf16_f32 v221, v142, v143
	v_cvt_pk_bf16_f32 v222, v136, v137
	v_permlane32_swap_b32_e32 v218, v219
	v_permlane32_swap_b32_e32 v128, v130
	v_cvt_pk_bf16_f32 v223, v223, v224
	v_permlane32_swap_b32_e32 v220, v222
	s_waitcnt lgkmcnt(3)
	v_mfma_f32_32x32x16_bf16 v[64:79], v[240:243], v[104:107], v[64:79]
	ds_read_b128 v[240:243], v190 offset:57344
	v_permlane32_swap_b32_e32 v129, v131
	v_permlane32_swap_b32_e32 v132, v134
	v_permlane32_swap_b32_e32 v133, v135
	v_permlane32_swap_b32_e32 v154, v156
	v_permlane32_swap_b32_e32 v155, v157
	v_permlane32_swap_b32_e32 v221, v223
	v_lshl_add_u64 v[136:137], s[100:101], 0, v[162:163]
	v_mul_lo_u32 v138, v137, s40
	s_waitcnt lgkmcnt(3)
	v_mfma_f32_32x32x16_bf16 v[80:95], v[244:247], v[100:103], v[80:95]
	ds_read_b128 v[244:247], v211
	v_mul_lo_u32 v139, v136, s41
	v_mad_u64_u32 v[136:137], s[6:7], v136, s40, 0
	v_add3_u32 v137, v137, v139, v138
	v_lshl_add_u64 v[138:139], v[166:167], 0, s[100:101]
	v_mul_lo_u32 v140, v139, s40
	v_mul_lo_u32 v141, v138, s41
	v_mad_u64_u32 v[138:139], s[6:7], v138, s40, 0
	v_add3_u32 v139, v139, v141, v140
	s_waitcnt lgkmcnt(3)
	v_mfma_f32_32x32x16_bf16 v[64:79], v[248:251], v[100:103], v[64:79]
	v_lshlrev_b64 v[146:147], 1, v[136:137]
	v_lshlrev_b64 v[148:149], 1, v[138:139]
	v_lshl_add_u64 v[158:159], s[100:101], 0, v[164:165]
	v_lshl_add_u64 v[136:137], v[168:169], 0, v[146:147]
	v_lshl_add_u64 v[140:141], v[168:169], 0, v[148:149]
	v_lshl_add_u64 v[146:147], v[170:171], 0, v[146:147]
	v_lshl_add_u64 v[150:151], v[170:171], 0, v[148:149]
	v_mad_u64_u32 v[160:161], s[100:101], v158, s3, v[172:173]
	global_load_dwordx4 v[136:139], v[136:137], off
	global_load_dwordx4 v[140:143], v[140:141], off
	global_load_dwordx4 v[146:149], v[146:147], off
	global_load_dwordx4 v[150:153], v[150:151], off
	v_mad_i32_i24 v161, v159, s3, v161
	global_load_dwordx4 v[158:161], v[160:161], off
	s_waitcnt lgkmcnt(2)
	v_mfma_f32_32x32x16_bf16 v[80:95], v[236:239], v[96:99], v[80:95]
	ds_read_b128 v[236:239], v211 offset:4096
	ds_read_b128 v[248:251], v182
	v_add_u32_e32 v252, 0x10800, v208
	s_waitcnt lgkmcnt(3)
	v_mfma_f32_32x32x16_bf16 v[64:79], v[240:243], v[96:99], v[64:79]
	ds_read_b128 v[240:243], v210
	s_waitcnt lgkmcnt(1)
	v_mfma_f32_32x32x16_bf16 v[80:95], v[244:247], v[248:251], v[80:95]
	v_mfma_f32_32x32x16_bf16 v[64:79], v[236:239], v[248:251], v[64:79]
	ds_read_b128 v[248:251], v210 offset:4096
	ds_read_b128 v[244:247], v182 offset:1024
	ds_read_b128 v[236:239], v216
	s_waitcnt lgkmcnt(1)
	v_mfma_f32_32x32x16_bf16 v[80:95], v[240:243], v[244:247], v[80:95]
	v_mfma_f32_32x32x16_bf16 v[64:79], v[248:251], v[244:247], v[64:79]
	ds_read_b128 v[244:247], v216 offset:4096
	ds_read_b128 v[240:243], v182 offset:2048
	ds_read_b128 v[248:251], v217
	s_waitcnt lgkmcnt(1)
	v_mfma_f32_32x32x16_bf16 v[80:95], v[236:239], v[240:243], v[80:95]
	v_mfma_f32_32x32x16_bf16 v[64:79], v[244:247], v[240:243], v[64:79]
	ds_read_b128 v[240:243], v217 offset:4096
	ds_read_b128 v[236:239], v182 offset:3072
	ds_read_b64_tr_b16 v[224:225], v181 offset:0
	ds_read_b64_tr_b16 v[226:227], v181 offset:0x800
	ds_read_b64_tr_b16 v[232:233], v181 offset:0x1000
	ds_read_b64_tr_b16 v[234:235], v181 offset:0x1800
	s_waitcnt lgkmcnt(4)
	v_mfma_f32_32x32x16_bf16 v[80:95], v[248:251], v[236:239], v[80:95]
	v_mfma_f32_32x32x16_bf16 v[64:79], v[240:243], v[236:239], v[64:79]
	ds_read_b64_tr_b16 v[236:237], v181 offset:0x2000
	ds_read_b64_tr_b16 v[238:239], v181 offset:0x2800
	ds_read_b64_tr_b16 v[240:241], v181 offset:0x3000
	ds_read_b64_tr_b16 v[242:243], v181 offset:0x3800
	ds_read_b64_tr_b16 v[212:213], v181 offset:0x200
	ds_read_b64_tr_b16 v[214:215], v181 offset:0xa00
	s_waitcnt lgkmcnt(8)
	v_mfma_f32_32x32x16_bf16 v[0:15], v[128:131], v[224:227], v[0:15]
	ds_read_b64_tr_b16 v[224:225], v181 offset:0x1200
	ds_read_b64_tr_b16 v[226:227], v181 offset:0x1a00
	s_waitcnt lgkmcnt(8)
	v_mfma_f32_32x32x16_bf16 v[0:15], v[132:135], v[232:235], v[0:15]
	ds_read_b64_tr_b16 v[232:233], v181 offset:0x2200
	ds_read_b64_tr_b16 v[234:235], v181 offset:0x2a00
	s_waitcnt lgkmcnt(8)
	v_mfma_f32_32x32x16_bf16 v[0:15], v[154:157], v[236:239], v[0:15]
	ds_read_b64_tr_b16 v[236:237], v181 offset:0x3200
	ds_read_b64_tr_b16 v[238:239], v181 offset:0x3a00
	v_max_f32_e32 v250, v81, v81
	v_max_f32_e32 v251, v80, v80
	v_max_f32_e32 v250, v251, v250
	v_max3_f32 v250, v250, v82, v83
	v_max3_f32 v250, v250, v84, v85
	v_max3_f32 v250, v250, v86, v87
	v_max3_f32 v250, v250, v88, v89
	v_max3_f32 v250, v250, v90, v91
	s_waitcnt lgkmcnt(8)
	v_mfma_f32_32x32x16_bf16 v[0:15], v[220:223], v[240:243], v[0:15]
	ds_read_b64_tr_b16 v[240:241], v181 offset:0x400
	ds_read_b64_tr_b16 v[242:243], v181 offset:0xc00
	v_max3_f32 v250, v250, v92, v93
	v_max3_f32 v250, v250, v94, v95
	v_max3_f32 v250, v250, v64, v65
	v_max3_f32 v250, v250, v66, v67
	v_max3_f32 v250, v250, v68, v69
	v_max3_f32 v250, v250, v70, v71
	v_max3_f32 v250, v250, v72, v73
	v_max3_f32 v250, v250, v74, v75
	s_waitcnt lgkmcnt(8)
	v_mfma_f32_32x32x16_bf16 v[48:63], v[128:131], v[212:215], v[48:63]
	ds_read_b64_tr_b16 v[212:213], v181 offset:0x1400
	ds_read_b64_tr_b16 v[214:215], v181 offset:0x1c00
	v_max3_f32 v250, v250, v76, v77
	v_max3_f32 v250, v250, v78, v79
	v_mov_b32_e32 v251, v250
	s_nop 1
	v_permlane32_swap_b32_e32 v250, v251
	v_max_f32_e32 v251, v251, v251
	v_max_f32_e32 v250, v250, v250
	v_max_f32_e32 v250, v250, v251
	v_sub_f32_e32 v251, v250, v207
	s_waitcnt lgkmcnt(8)
	v_mfma_f32_32x32x16_bf16 v[48:63], v[132:135], v[224:227], v[48:63]
	ds_read_b64_tr_b16 v[224:225], v181 offset:0x2400
	ds_read_b64_tr_b16 v[226:227], v181 offset:0x2c00
	v_cmp_ge_f32_e32 vcc, s94, v251
	v_max_f32_e32 v251, v207, v207
	v_max_f32_e32 v250, v251, v250
	v_sub_f32_e32 v251, v207, v250
	v_mul_f32_e32 v251, 0x3dd53b94, v251
	v_exp_f32_e32 v251, v251
	s_waitcnt lgkmcnt(8)
	v_mfma_f32_32x32x16_bf16 v[48:63], v[154:157], v[232:235], v[48:63]
	ds_read_b64_tr_b16 v[232:233], v181 offset:0x3400
	ds_read_b64_tr_b16 v[234:235], v181 offset:0x3c00
	s_waitcnt lgkmcnt(8)
	v_mfma_f32_32x32x16_bf16 v[48:63], v[220:223], v[236:239], v[48:63]
	ds_read_b64_tr_b16 v[236:237], v181 offset:0x600
	ds_read_b64_tr_b16 v[238:239], v181 offset:0xe00
	s_waitcnt lgkmcnt(8)
	v_mfma_f32_32x32x16_bf16 v[32:47], v[128:131], v[240:243], v[32:47]
	ds_read_b64_tr_b16 v[240:241], v181 offset:0x1600
	ds_read_b64_tr_b16 v[242:243], v181 offset:0x1e00
	s_waitcnt lgkmcnt(8)
	v_mfma_f32_32x32x16_bf16 v[32:47], v[132:135], v[212:215], v[32:47]
	ds_read_b64_tr_b16 v[212:213], v181 offset:0x2600
	ds_read_b64_tr_b16 v[214:215], v181 offset:0x2e00
	s_waitcnt vmcnt(0)
	ds_write_b128 v187, v[146:149] offset:32768
	ds_write_b128 v188, v[150:153] offset:32768
	ds_write_b128 v252, v[158:161]
	s_waitcnt lgkmcnt(11)
	v_mfma_f32_32x32x16_bf16 v[32:47], v[154:157], v[224:227], v[32:47]
	ds_read_b64_tr_b16 v[224:225], v181 offset:0x3600
	ds_read_b64_tr_b16 v[226:227], v181 offset:0x3e00
	s_waitcnt lgkmcnt(11)
	v_mfma_f32_32x32x16_bf16 v[32:47], v[220:223], v[232:235], v[32:47]
	s_waitcnt lgkmcnt(9)
	v_mfma_f32_32x32x16_bf16 v[16:31], v[128:131], v[236:239], v[16:31]
	s_waitcnt lgkmcnt(7)
	v_mfma_f32_32x32x16_bf16 v[16:31], v[132:135], v[240:243], v[16:31]
	s_waitcnt lgkmcnt(5)
	v_mfma_f32_32x32x16_bf16 v[16:31], v[154:157], v[212:215], v[16:31]
	s_waitcnt lgkmcnt(0)
	v_mfma_f32_32x32x16_bf16 v[16:31], v[220:223], v[224:227], v[16:31]
	s_cmp_eq_u64 vcc, exec
	s_cselect_b64 s[6:7], -1, 0
	s_barrier
	v_cndmask_b32_e64 v220, v251, 1.0, s[6:7]
	v_cmp_gt_f32_e32 vcc, 1.0, v220
	ds_write_b128 v185, v[136:139]
	ds_write_b128 v186, v[140:143]
	s_cbranch_vccz .LBB0_766
	s_and_saveexec_b64 s[0:1], s[4:5]
	ds_write_b32 v183, v220 offset:128
	s_or_b64 exec, exec, s[0:1]
	s_waitcnt lgkmcnt(0)
	v_add_u32_e32 v129, v180, v144
	ds_read_b128 v[130:133], v129 offset:224
	ds_read_b128 v[134:137], v129 offset:192
	ds_read_b128 v[138:141], v129 offset:160
	ds_read_b128 v[146:149], v129 offset:128
	s_waitcnt lgkmcnt(3)
	v_pk_mul_f32 v[12:13], v[12:13], v[130:131]
	s_waitcnt lgkmcnt(2)
	v_pk_mul_f32 v[8:9], v[8:9], v[134:135]
	s_waitcnt lgkmcnt(1)
	v_pk_mul_f32 v[4:5], v[4:5], v[138:139]
	v_pk_mul_f32 v[14:15], v[14:15], v[132:133]
	v_pk_mul_f32 v[10:11], v[10:11], v[136:137]
	v_pk_mul_f32 v[6:7], v[6:7], v[140:141]
	s_waitcnt lgkmcnt(0)
	v_pk_mul_f32 v[2:3], v[2:3], v[148:149]
	v_pk_mul_f32 v[0:1], v[0:1], v[146:147]
	v_pk_mul_f32 v[60:61], v[60:61], v[130:131]
	v_pk_mul_f32 v[56:57], v[56:57], v[134:135]
	v_pk_mul_f32 v[52:53], v[52:53], v[138:139]
	v_pk_mul_f32 v[62:63], v[62:63], v[132:133]
	v_pk_mul_f32 v[58:59], v[58:59], v[136:137]
	v_pk_mul_f32 v[54:55], v[54:55], v[140:141]
	v_pk_mul_f32 v[50:51], v[50:51], v[148:149]
	v_pk_mul_f32 v[48:49], v[48:49], v[146:147]
	v_pk_mul_f32 v[44:45], v[44:45], v[130:131]
	v_pk_mul_f32 v[40:41], v[40:41], v[134:135]
	v_pk_mul_f32 v[36:37], v[36:37], v[138:139]
	v_pk_mul_f32 v[46:47], v[46:47], v[132:133]
	v_pk_mul_f32 v[42:43], v[42:43], v[136:137]
	v_pk_mul_f32 v[38:39], v[38:39], v[140:141]
	v_pk_mul_f32 v[34:35], v[34:35], v[148:149]
	v_pk_mul_f32 v[32:33], v[32:33], v[146:147]
	v_pk_mul_f32 v[28:29], v[28:29], v[130:131]
	v_pk_mul_f32 v[24:25], v[24:25], v[134:135]
	v_pk_mul_f32 v[20:21], v[20:21], v[138:139]
	v_pk_mul_f32 v[30:31], v[30:31], v[132:133]
	v_pk_mul_f32 v[26:27], v[26:27], v[136:137]
	v_pk_mul_f32 v[22:23], v[22:23], v[140:141]
	v_pk_mul_f32 v[18:19], v[18:19], v[148:149]
	v_pk_mul_f32 v[16:17], v[16:17], v[146:147]
.LBB0_766:
	v_cndmask_b32_e64 v207, v250, v207, s[6:7]
	v_mul_f32_e32 v146, 0xbdd53b94, v207
	v_fmamk_f32 v80, v80, 0x3dd53b94, v146
	v_exp_f32_e32 v128, v80
	v_fmamk_f32 v81, v81, 0x3dd53b94, v146
	v_fmamk_f32 v82, v82, 0x3dd53b94, v146
	v_fmamk_f32 v83, v83, 0x3dd53b94, v146
	v_fmamk_f32 v84, v84, 0x3dd53b94, v146
	v_fmamk_f32 v85, v85, 0x3dd53b94, v146
	v_fmamk_f32 v86, v86, 0x3dd53b94, v146
	v_fmamk_f32 v87, v87, 0x3dd53b94, v146
	v_fmamk_f32 v88, v88, 0x3dd53b94, v146
	v_fmamk_f32 v89, v89, 0x3dd53b94, v146
	v_fmamk_f32 v90, v90, 0x3dd53b94, v146
	v_fmamk_f32 v91, v91, 0x3dd53b94, v146
	v_fmamk_f32 v92, v92, 0x3dd53b94, v146
	v_fmamk_f32 v93, v93, 0x3dd53b94, v146
	v_fmamk_f32 v94, v94, 0x3dd53b94, v146
	v_fmamk_f32 v95, v95, 0x3dd53b94, v146
	v_fmamk_f32 v155, v64, 0x3dd53b94, v146
	v_fmamk_f32 v156, v65, 0x3dd53b94, v146
	v_fmamk_f32 v157, v66, 0x3dd53b94, v146
	v_fmamk_f32 v158, v67, 0x3dd53b94, v146
	v_fmamk_f32 v159, v68, 0x3dd53b94, v146
	v_fmamk_f32 v148, v69, 0x3dd53b94, v146
	v_fmamk_f32 v149, v70, 0x3dd53b94, v146
	v_fmamk_f32 v150, v71, 0x3dd53b94, v146
	v_fmamk_f32 v151, v72, 0x3dd53b94, v146
	v_fmamk_f32 v152, v73, 0x3dd53b94, v146
	v_fmamk_f32 v153, v74, 0x3dd53b94, v146
	v_fmamk_f32 v154, v75, 0x3dd53b94, v146
	v_fmamk_f32 v147, v76, 0x3dd53b94, v146
	v_exp_f32_e32 v143, v81
	v_exp_f32_e32 v129, v82
	v_exp_f32_e32 v142, v83
	v_exp_f32_e32 v130, v84
	v_exp_f32_e32 v141, v85
	v_exp_f32_e32 v131, v86
	v_exp_f32_e32 v140, v87
	v_exp_f32_e32 v132, v88
	v_exp_f32_e32 v139, v89
	v_exp_f32_e32 v133, v90
	v_exp_f32_e32 v138, v91
	v_exp_f32_e32 v134, v92
	v_exp_f32_e32 v137, v93
	v_exp_f32_e32 v135, v94
	v_exp_f32_e32 v136, v95
	v_fmamk_f32 v160, v77, 0x3dd53b94, v146
	v_fmamk_f32 v161, v78, 0x3dd53b94, v146
	v_fmac_f32_e32 v146, 0x3dd53b94, v79
	ds_read_b128 v[64:67], v189 offset:32768
	ds_read_b128 v[68:71], v189 offset:40960
	ds_read_b128 v[240:243], v191 offset:32768
	ds_read_b128 v[244:247], v191 offset:40960
	ds_read_b128 v[248:251], v193 offset:32768
	s_cmp_lt_u32 s9, 2
	s_cselect_b32 s100, s46, s68
	s_add_i32 s100, s100, s8
	s_add_i32 s100, s100, 64
	s_ashr_i32 s101, s100, 31
	s_waitcnt lgkmcnt(4)
	v_mfma_f32_32x32x16_bf16 v[80:95], v[64:67], v[124:127], 0
	v_exp_f32_e32 v212, v154
	v_add_f32_e32 v154, 0, v128
	v_add_f32_e32 v154, v143, v154
	v_add_f32_e32 v154, v129, v154
	v_add_f32_e32 v154, v142, v154
	v_add_f32_e32 v154, v130, v154
	v_add_f32_e32 v154, v141, v154
	s_waitcnt lgkmcnt(3)
	v_mfma_f32_32x32x16_bf16 v[64:79], v[68:71], v[124:127], 0
	v_add_f32_e32 v154, v131, v154
	v_add_f32_e32 v154, v140, v154
	v_add_f32_e32 v154, v132, v154
	v_add_f32_e32 v154, v139, v154
	v_add_f32_e32 v154, v133, v154
	v_add_f32_e32 v154, v138, v154
	v_exp_f32_e32 v155, v155
	s_waitcnt lgkmcnt(2)
	v_mfma_f32_32x32x16_bf16 v[80:95], v[240:243], v[120:123], v[80:95]
	ds_read_b128 v[240:243], v193 offset:40960
	v_add_f32_e32 v154, v134, v154
	v_exp_f32_e32 v156, v156
	v_add_f32_e32 v154, v137, v154
	v_exp_f32_e32 v157, v157
	v_add_f32_e32 v154, v135, v154
	v_add_f32_e32 v154, v136, v154
	s_waitcnt lgkmcnt(2)
	v_mfma_f32_32x32x16_bf16 v[64:79], v[244:247], v[120:123], v[64:79]
	ds_read_b128 v[244:247], v195 offset:32768
	v_exp_f32_e32 v158, v158
	v_exp_f32_e32 v159, v159
	v_add_f32_e32 v154, v155, v154
	v_exp_f32_e32 v148, v148
	v_add_f32_e32 v154, v156, v154
	s_waitcnt lgkmcnt(2)
	v_mfma_f32_32x32x16_bf16 v[80:95], v[248:251], v[116:119], v[80:95]
	ds_read_b128 v[248:251], v195 offset:40960
	v_exp_f32_e32 v149, v149
	v_add_f32_e32 v154, v157, v154
	v_exp_f32_e32 v150, v150
	v_add_f32_e32 v154, v158, v154
	v_exp_f32_e32 v151, v151
	s_waitcnt lgkmcnt(2)
	v_mfma_f32_32x32x16_bf16 v[64:79], v[240:243], v[116:119], v[64:79]
	ds_read_b128 v[240:243], v196 offset:32768
	v_add_f32_e32 v154, v159, v154
	v_exp_f32_e32 v152, v152
	v_add_f32_e32 v154, v148, v154
	v_exp_f32_e32 v153, v153
	v_add_f32_e32 v154, v149, v154
	v_add_f32_e32 v154, v150, v154
	s_waitcnt lgkmcnt(2)
	v_mfma_f32_32x32x16_bf16 v[80:95], v[244:247], v[112:115], v[80:95]
	ds_read_b128 v[244:247], v196 offset:40960
	v_exp_f32_e32 v147, v147
	v_add_f32_e32 v154, v151, v154
	v_exp_f32_e32 v160, v160
	v_add_f32_e32 v154, v152, v154
	v_exp_f32_e32 v161, v161
	s_waitcnt lgkmcnt(2)
	v_mfma_f32_32x32x16_bf16 v[64:79], v[248:251], v[112:115], v[64:79]
	ds_read_b128 v[248:251], v194 offset:32768
	v_add_f32_e32 v154, v153, v154
	v_exp_f32_e32 v146, v146
	v_add_f32_e32 v154, v212, v154
	v_add_f32_e32 v154, v147, v154
	v_add_f32_e32 v154, v160, v154
	v_add_f32_e32 v154, v161, v154
	v_cvt_pk_bf16_f32 v128, v128, v143
	s_waitcnt lgkmcnt(2)
	v_mfma_f32_32x32x16_bf16 v[80:95], v[240:243], v[108:111], v[80:95]
	ds_read_b128 v[240:243], v194 offset:40960
	v_cvt_pk_bf16_f32 v129, v129, v142
	v_cvt_pk_bf16_f32 v130, v130, v141
	v_cvt_pk_bf16_f32 v131, v131, v140
	v_cvt_pk_bf16_f32 v132, v132, v139
	v_cvt_pk_bf16_f32 v133, v133, v138
	v_add_f32_e32 v222, v146, v154
	v_mov_b32_e32 v223, v222
	s_nop 1
	v_permlane32_swap_b32_e32 v222, v223
	s_waitcnt lgkmcnt(2)
	v_mfma_f32_32x32x16_bf16 v[64:79], v[244:247], v[108:111], v[64:79]
	ds_read_b128 v[244:247], v192 offset:32768
	v_permlane32_swap_b32_e32 v128, v130
	v_cvt_pk_bf16_f32 v134, v134, v137
	v_cvt_pk_bf16_f32 v135, v135, v136
	v_cvt_pk_bf16_f32 v154, v155, v156
	v_cvt_pk_bf16_f32 v155, v157, v158
	v_cvt_pk_bf16_f32 v156, v159, v148
	v_cvt_pk_bf16_f32 v157, v149, v150
	v_cvt_pk_bf16_f32 v224, v151, v152
	s_waitcnt lgkmcnt(2)
	v_mfma_f32_32x32x16_bf16 v[80:95], v[248:251], v[104:107], v[80:95]
	ds_read_b128 v[248:251], v192 offset:40960
	v_cvt_pk_bf16_f32 v225, v153, v212
	v_cvt_pk_bf16_f32 v226, v147, v160
	v_cvt_pk_bf16_f32 v227, v161, v146
	v_permlane32_swap_b32_e32 v129, v131
	v_permlane32_swap_b32_e32 v132, v134
	v_permlane32_swap_b32_e32 v133, v135
	v_permlane32_swap_b32_e32 v154, v156
	v_permlane32_swap_b32_e32 v155, v157
	s_waitcnt lgkmcnt(2)
	v_mfma_f32_32x32x16_bf16 v[64:79], v[240:243], v[104:107], v[64:79]
	ds_read_b128 v[240:243], v190 offset:32768
	v_permlane32_swap_b32_e32 v224, v226
	v_permlane32_swap_b32_e32 v225, v227
	v_lshl_add_u64 v[136:137], s[100:101], 0, v[162:163]
	v_mul_lo_u32 v138, v137, s40
	v_mul_lo_u32 v139, v136, s41
	v_mad_u64_u32 v[136:137], s[6:7], v136, s40, 0
	v_add3_u32 v137, v137, v139, v138
	v_lshl_add_u64 v[138:139], v[166:167], 0, s[100:101]
	s_waitcnt lgkmcnt(2)
	v_mfma_f32_32x32x16_bf16 v[80:95], v[244:247], v[100:103], v[80:95]
	ds_read_b128 v[244:247], v190 offset:40960
	v_mul_lo_u32 v140, v139, s40
	v_mul_lo_u32 v141, v138, s41
	v_mad_u64_u32 v[138:139], s[6:7], v138, s40, 0
	v_add3_u32 v139, v139, v141, v140
	v_lshlrev_b64 v[146:147], 1, v[136:137]
	v_lshlrev_b64 v[148:149], 1, v[138:139]
	v_lshl_add_u64 v[158:159], s[100:101], 0, v[164:165]
	v_lshl_add_u64 v[136:137], v[168:169], 0, v[146:147]
	global_load_dwordx4 v[136:139], v[136:137], off
	v_lshl_add_u64 v[140:141], v[168:169], 0, v[148:149]
	global_load_dwordx4 v[140:143], v[140:141], off
	v_lshl_add_u64 v[146:147], v[170:171], 0, v[146:147]
	v_lshl_add_u64 v[150:151], v[170:171], 0, v[148:149]
	global_load_dwordx4 v[146:149], v[146:147], off
	global_load_dwordx4 v[150:153], v[150:151], off
	s_waitcnt lgkmcnt(2)
	v_mfma_f32_32x32x16_bf16 v[64:79], v[248:251], v[100:103], v[64:79]
	ds_read_b128 v[248:251], v199
	v_mad_u64_u32 v[160:161], s[100:101], v158, s3, v[172:173]
	v_mad_i32_i24 v161, v159, s3, v161
	global_load_dwordx4 v[158:161], v[160:161], off
	s_waitcnt lgkmcnt(2)
	v_mfma_f32_32x32x16_bf16 v[80:95], v[240:243], v[96:99], v[80:95]
	s_waitcnt lgkmcnt(1)
	v_mfma_f32_32x32x16_bf16 v[64:79], v[244:247], v[96:99], v[64:79]
	ds_read_b128 v[244:247], v199 offset:4096
	ds_read_b128 v[240:243], v182
	s_waitcnt lgkmcnt(0)
	v_mfma_f32_32x32x16_bf16 v[80:95], v[248:251], v[240:243], v[80:95]
	ds_read_b128 v[248:251], v201
	v_mfma_f32_32x32x16_bf16 v[64:79], v[244:247], v[240:243], v[64:79]
	ds_read_b128 v[244:247], v201 offset:4096
	ds_read_b128 v[240:243], v182 offset:1024
	s_waitcnt lgkmcnt(0)
	v_mfma_f32_32x32x16_bf16 v[80:95], v[248:251], v[240:243], v[80:95]
	ds_read_b128 v[248:251], v203
	v_mfma_f32_32x32x16_bf16 v[64:79], v[244:247], v[240:243], v[64:79]
	ds_read_b128 v[244:247], v203 offset:4096
	ds_read_b128 v[240:243], v182 offset:2048
	s_waitcnt lgkmcnt(0)
	v_mfma_f32_32x32x16_bf16 v[80:95], v[248:251], v[240:243], v[80:95]
	ds_read_b128 v[248:251], v205
	v_mfma_f32_32x32x16_bf16 v[64:79], v[244:247], v[240:243], v[64:79]
	ds_read_b128 v[244:247], v205 offset:4096
	ds_read_b128 v[240:243], v182 offset:3072
	ds_read_b64_tr_b16 v[232:233], v184 offset:0
	ds_read_b64_tr_b16 v[234:235], v184 offset:0x800
	ds_read_b64_tr_b16 v[236:237], v184 offset:0x1000
	ds_read_b64_tr_b16 v[238:239], v184 offset:0x1800
	s_waitcnt lgkmcnt(4)
	v_mfma_f32_32x32x16_bf16 v[80:95], v[248:251], v[240:243], v[80:95]
	v_mfma_f32_32x32x16_bf16 v[64:79], v[244:247], v[240:243], v[64:79]
	ds_read_b64_tr_b16 v[240:241], v184 offset:0x2000
	ds_read_b64_tr_b16 v[242:243], v184 offset:0x2800
	ds_read_b64_tr_b16 v[244:245], v184 offset:0x3000
	ds_read_b64_tr_b16 v[246:247], v184 offset:0x3800
	s_waitcnt lgkmcnt(6)
	v_mfma_f32_32x32x16_bf16 v[0:15], v[128:131], v[232:235], v[0:15]
	ds_read_b64_tr_b16 v[232:233], v184 offset:0x200
	ds_read_b64_tr_b16 v[234:235], v184 offset:0xa00
	s_waitcnt lgkmcnt(6)
	v_mfma_f32_32x32x16_bf16 v[0:15], v[132:135], v[236:239], v[0:15]
	ds_read_b64_tr_b16 v[236:237], v184 offset:0x1200
	ds_read_b64_tr_b16 v[238:239], v184 offset:0x1a00
	s_waitcnt lgkmcnt(6)
	v_mfma_f32_32x32x16_bf16 v[0:15], v[154:157], v[240:243], v[0:15]
	ds_read_b64_tr_b16 v[240:241], v184 offset:0x2200
	ds_read_b64_tr_b16 v[242:243], v184 offset:0x2a00
	v_max_f32_e32 v250, v81, v81
	v_max_f32_e32 v251, v80, v80
	v_max_f32_e32 v250, v251, v250
	v_max3_f32 v250, v250, v82, v83
	v_max3_f32 v250, v250, v84, v85
	v_max3_f32 v250, v250, v86, v87
	v_max3_f32 v250, v250, v88, v89
	v_max3_f32 v250, v250, v90, v91
	s_waitcnt lgkmcnt(6)
	v_mfma_f32_32x32x16_bf16 v[0:15], v[224:227], v[244:247], v[0:15]
	ds_read_b64_tr_b16 v[244:245], v184 offset:0x3200
	ds_read_b64_tr_b16 v[246:247], v184 offset:0x3a00
	v_max3_f32 v250, v250, v92, v93
	v_max3_f32 v250, v250, v94, v95
	v_max3_f32 v250, v250, v64, v65
	v_max3_f32 v250, v250, v66, v67
	v_max3_f32 v250, v250, v68, v69
	v_max3_f32 v250, v250, v70, v71
	v_max3_f32 v250, v250, v72, v73
	v_max3_f32 v250, v250, v74, v75
	s_waitcnt lgkmcnt(6)
	v_mfma_f32_32x32x16_bf16 v[48:63], v[128:131], v[232:235], v[48:63]
	ds_read_b64_tr_b16 v[232:233], v184 offset:0x400
	ds_read_b64_tr_b16 v[234:235], v184 offset:0xc00
	v_max3_f32 v250, v250, v76, v77
	v_max3_f32 v250, v250, v78, v79
	v_mov_b32_e32 v251, v250
	s_nop 1
	v_permlane32_swap_b32_e32 v250, v251
	v_max_f32_e32 v251, v251, v251
	v_max_f32_e32 v250, v250, v250
	v_max_f32_e32 v250, v250, v251
	v_sub_f32_e32 v251, v250, v207
	s_waitcnt lgkmcnt(6)
	v_mfma_f32_32x32x16_bf16 v[48:63], v[132:135], v[236:239], v[48:63]
	ds_read_b64_tr_b16 v[236:237], v184 offset:0x1400
	ds_read_b64_tr_b16 v[238:239], v184 offset:0x1c00
	v_cmp_ge_f32_e32 vcc, s94, v251
	v_max_f32_e32 v251, v207, v207
	v_max_f32_e32 v250, v251, v250
	v_sub_f32_e32 v251, v207, v250
	v_mul_f32_e32 v251, 0x3dd53b94, v251
	v_exp_f32_e32 v251, v251
	s_waitcnt lgkmcnt(6)
	v_mfma_f32_32x32x16_bf16 v[48:63], v[154:157], v[240:243], v[48:63]
	ds_read_b64_tr_b16 v[240:241], v184 offset:0x2400
	ds_read_b64_tr_b16 v[242:243], v184 offset:0x2c00
	s_waitcnt lgkmcnt(6)
	v_mfma_f32_32x32x16_bf16 v[48:63], v[224:227], v[244:247], v[48:63]
	ds_read_b64_tr_b16 v[244:245], v184 offset:0x3400
	ds_read_b64_tr_b16 v[246:247], v184 offset:0x3c00
	s_waitcnt lgkmcnt(6)
	v_mfma_f32_32x32x16_bf16 v[32:47], v[128:131], v[232:235], v[32:47]
	ds_read_b64_tr_b16 v[232:233], v184 offset:0x600
	ds_read_b64_tr_b16 v[234:235], v184 offset:0xe00
	s_waitcnt lgkmcnt(6)
	v_mfma_f32_32x32x16_bf16 v[32:47], v[132:135], v[236:239], v[32:47]
	ds_read_b64_tr_b16 v[236:237], v184 offset:0x1600
	ds_read_b64_tr_b16 v[238:239], v184 offset:0x1e00
	s_waitcnt vmcnt(0)
	ds_write_b128 v187, v[146:149] offset:49152
	ds_write_b128 v188, v[150:153] offset:49152
	ds_write_b128 v209, v[158:161]
	s_waitcnt lgkmcnt(9)
	v_mfma_f32_32x32x16_bf16 v[32:47], v[154:157], v[240:243], v[32:47]
	ds_read_b64_tr_b16 v[240:241], v184 offset:0x2600
	ds_read_b64_tr_b16 v[242:243], v184 offset:0x2e00
	s_waitcnt lgkmcnt(9)
	v_mfma_f32_32x32x16_bf16 v[32:47], v[224:227], v[244:247], v[32:47]
	ds_read_b64_tr_b16 v[244:245], v184 offset:0x3600
	ds_read_b64_tr_b16 v[246:247], v184 offset:0x3e00
	s_waitcnt lgkmcnt(9)
	v_mfma_f32_32x32x16_bf16 v[16:31], v[128:131], v[232:235], v[16:31]
	s_waitcnt lgkmcnt(7)
	v_mfma_f32_32x32x16_bf16 v[16:31], v[132:135], v[236:239], v[16:31]
	s_waitcnt lgkmcnt(2)
	v_mfma_f32_32x32x16_bf16 v[16:31], v[154:157], v[240:243], v[16:31]
	s_waitcnt lgkmcnt(0)
	v_mfma_f32_32x32x16_bf16 v[16:31], v[224:227], v[244:247], v[16:31]
	s_cmp_eq_u64 vcc, exec
	s_cselect_b64 s[6:7], -1, 0
	s_barrier
	v_cndmask_b32_e64 v221, v251, 1.0, s[6:7]
	v_cmp_gt_f32_e32 vcc, 1.0, v221
	ds_write_b128 v185, v[136:139] offset:16384
	ds_write_b128 v186, v[140:143] offset:16384
	s_cbranch_vccz .LBB0_770
	s_and_saveexec_b64 s[0:1], s[4:5]
	ds_write_b32 v183, v221 offset:128
	s_or_b64 exec, exec, s[0:1]
	s_waitcnt lgkmcnt(0)
	v_add_u32_e32 v129, v180, v144
	ds_read_b128 v[130:133], v129 offset:224
	ds_read_b128 v[134:137], v129 offset:192
	ds_read_b128 v[138:141], v129 offset:160
	ds_read_b128 v[146:149], v129 offset:128
	s_waitcnt lgkmcnt(3)
	v_pk_mul_f32 v[12:13], v[12:13], v[130:131]
	s_waitcnt lgkmcnt(2)
	v_pk_mul_f32 v[8:9], v[8:9], v[134:135]
	s_waitcnt lgkmcnt(1)
	v_pk_mul_f32 v[4:5], v[4:5], v[138:139]
	v_pk_mul_f32 v[14:15], v[14:15], v[132:133]
	v_pk_mul_f32 v[10:11], v[10:11], v[136:137]
	v_pk_mul_f32 v[6:7], v[6:7], v[140:141]
	s_waitcnt lgkmcnt(0)
	v_pk_mul_f32 v[2:3], v[2:3], v[148:149]
	v_pk_mul_f32 v[0:1], v[0:1], v[146:147]
	v_pk_mul_f32 v[60:61], v[60:61], v[130:131]
	v_pk_mul_f32 v[56:57], v[56:57], v[134:135]
	v_pk_mul_f32 v[52:53], v[52:53], v[138:139]
	v_pk_mul_f32 v[62:63], v[62:63], v[132:133]
	v_pk_mul_f32 v[58:59], v[58:59], v[136:137]
	v_pk_mul_f32 v[54:55], v[54:55], v[140:141]
	v_pk_mul_f32 v[50:51], v[50:51], v[148:149]
	v_pk_mul_f32 v[48:49], v[48:49], v[146:147]
	v_pk_mul_f32 v[44:45], v[44:45], v[130:131]
	v_pk_mul_f32 v[40:41], v[40:41], v[134:135]
	v_pk_mul_f32 v[36:37], v[36:37], v[138:139]
	v_pk_mul_f32 v[46:47], v[46:47], v[132:133]
	v_pk_mul_f32 v[42:43], v[42:43], v[136:137]
	v_pk_mul_f32 v[38:39], v[38:39], v[140:141]
	v_pk_mul_f32 v[34:35], v[34:35], v[148:149]
	v_pk_mul_f32 v[32:33], v[32:33], v[146:147]
	v_pk_mul_f32 v[28:29], v[28:29], v[130:131]
	v_pk_mul_f32 v[24:25], v[24:25], v[134:135]
	v_pk_mul_f32 v[20:21], v[20:21], v[138:139]
	v_pk_mul_f32 v[30:31], v[30:31], v[132:133]
	v_pk_mul_f32 v[26:27], v[26:27], v[136:137]
	v_pk_mul_f32 v[22:23], v[22:23], v[140:141]
	v_pk_mul_f32 v[18:19], v[18:19], v[148:149]
	v_pk_mul_f32 v[16:17], v[16:17], v[146:147]
.LBB0_770:
	v_cndmask_b32_e64 v207, v250, v207, s[6:7]
	v_mul_f32_e32 v134, 0xbdd53b94, v207
	v_mov_b32_e32 v135, v134
	v_fmamk_f32 v80, v80, 0x3dd53b94, v134
	v_fmamk_f32 v81, v81, 0x3dd53b94, v134
	v_fmamk_f32 v82, v82, 0x3dd53b94, v134
	v_fmamk_f32 v83, v83, 0x3dd53b94, v134
	v_fmamk_f32 v84, v84, 0x3dd53b94, v134
	v_fmamk_f32 v85, v85, 0x3dd53b94, v134
	v_fmamk_f32 v86, v86, 0x3dd53b94, v134
	v_fmamk_f32 v87, v87, 0x3dd53b94, v134
	v_fmamk_f32 v88, v88, 0x3dd53b94, v134
	v_fmamk_f32 v89, v89, 0x3dd53b94, v134
	v_fmamk_f32 v90, v90, 0x3dd53b94, v134
	v_fmamk_f32 v91, v91, 0x3dd53b94, v134
	v_fmamk_f32 v92, v92, 0x3dd53b94, v134
	v_fmamk_f32 v93, v93, 0x3dd53b94, v134
	v_fmamk_f32 v94, v94, 0x3dd53b94, v134
	v_fmac_f32_e32 v135, 0x3dd53b94, v95
	v_exp_f32_e32 v159, v80
	v_exp_f32_e32 v161, v81
	v_exp_f32_e32 v157, v82
	v_exp_f32_e32 v160, v83
	v_exp_f32_e32 v156, v84
	v_exp_f32_e32 v158, v85
	v_exp_f32_e32 v154, v86
	v_exp_f32_e32 v155, v87
	v_exp_f32_e32 v151, v88
	v_exp_f32_e32 v153, v89
	v_exp_f32_e32 v150, v90
	v_exp_f32_e32 v152, v91
	v_exp_f32_e32 v147, v92
	v_exp_f32_e32 v149, v93
	v_exp_f32_e32 v146, v94
	v_exp_f32_e32 v148, v135
	v_pk_fma_f32 v[140:141], v[64:65], s[76:77], v[134:135] op_sel_hi:[1,0,0]
	v_add_f32_e32 v64, v218, v219
	v_fmac_f32_e32 v64, v206, v197
	v_add_f32_e32 v197, v222, v223
	s_addk_i32 s8, 0x80
	s_add_i32 s24, s24, 2
	v_pk_fma_f32 v[138:139], v[66:67], s[76:77], v[134:135] op_sel_hi:[1,0,0]
	v_pk_fma_f32 v[132:133], v[68:69], s[76:77], v[134:135] op_sel_hi:[1,0,0]
	v_pk_fma_f32 v[130:131], v[70:71], s[76:77], v[134:135] op_sel_hi:[1,0,0]
	v_pk_fma_f32 v[128:129], v[72:73], s[76:77], v[134:135] op_sel_hi:[1,0,0]
	v_pk_fma_f32 v[142:143], v[74:75], s[76:77], v[134:135] op_sel_hi:[1,0,0]
	v_pk_fma_f32 v[136:137], v[76:77], s[76:77], v[134:135] op_sel_hi:[1,0,0]
	v_pk_fma_f32 v[134:135], v[78:79], s[76:77], v[134:135] op_sel_hi:[1,0,0]
	v_fmac_f32_e32 v197, v64, v220
	s_cmp_ge_u32 s24, s91
	s_cbranch_scc1 .LBB0_772
	v_mov_b32_e32 v206, v221
	s_branch .LBB0_762
